# attention loop head trimmed further: LDS slot bases toggled at the previous tail, redundant guard compares dropped, -slope2 hoisted (on top of pre-biased addresses + per-half copies)
# speedup vs baseline: 1.0039x; 1.0039x over previous
.Lan_entry:
	v_cvt_f32_i32_e32 v255, v231
	v_add_f32_e32 v255, 0x42800000, v255
	v_cmp_eq_u32_e32 vcc, 0, v203
	s_nop 1
	v_cndmask_b32_e32 v208, v229, v255, vcc
	v_add_f32_e32 v255, 0x80000000, v208
	v_fma_f32 v96, -v201, |v255|, v253
	v_add_f32_e32 v255, 0xbf800000, v208
	v_fma_f32 v97, -v201, |v255|, v253
	v_add_f32_e32 v255, 0xc0000000, v208
	v_fma_f32 v98, -v201, |v255|, v253
	v_add_f32_e32 v255, 0xc0400000, v208
	v_fma_f32 v99, -v201, |v255|, v253
	v_add_f32_e32 v255, 0xc0800000, v208
	v_fma_f32 v100, -v201, |v255|, v253
	v_add_f32_e32 v255, 0xc0a00000, v208
	v_fma_f32 v101, -v201, |v255|, v253
	v_add_f32_e32 v255, 0xc0c00000, v208
	v_fma_f32 v102, -v201, |v255|, v253
	v_add_f32_e32 v255, 0xc0e00000, v208
	v_fma_f32 v103, -v201, |v255|, v253
	v_add_f32_e32 v255, 0xc1800000, v208
	v_fma_f32 v104, -v201, |v255|, v253
	v_add_f32_e32 v255, 0xc1880000, v208
	v_fma_f32 v105, -v201, |v255|, v253
	v_add_f32_e32 v255, 0xc1900000, v208
	v_fma_f32 v106, -v201, |v255|, v253
	v_add_f32_e32 v255, 0xc1980000, v208
	v_fma_f32 v107, -v201, |v255|, v253
	v_add_f32_e32 v255, 0xc1a00000, v208
	v_fma_f32 v108, -v201, |v255|, v253
	v_add_f32_e32 v255, 0xc1a80000, v208
	v_fma_f32 v109, -v201, |v255|, v253
	v_add_f32_e32 v255, 0xc1b00000, v208
	v_fma_f32 v110, -v201, |v255|, v253
	v_add_f32_e32 v255, 0xc1b80000, v208
	v_fma_f32 v111, -v201, |v255|, v253
	v_mov_b32_e32 v80, 0xff61b1e6
	v_mov_b32_e32 v81, 0xff61b1e6
	v_mov_b32_e32 v82, 0xff61b1e6
	v_mov_b32_e32 v83, 0xff61b1e6
	v_mov_b32_e32 v84, 0xff61b1e6
	v_mov_b32_e32 v85, 0xff61b1e6
	v_mov_b32_e32 v86, 0xff61b1e6
	v_mov_b32_e32 v87, 0xff61b1e6
	v_mov_b32_e32 v88, 0xff61b1e6
	v_mov_b32_e32 v89, 0xff61b1e6
	v_mov_b32_e32 v90, 0xff61b1e6
	v_mov_b32_e32 v91, 0xff61b1e6
	v_mov_b32_e32 v92, 0xff61b1e6
	v_mov_b32_e32 v93, 0xff61b1e6
	v_mov_b32_e32 v94, 0xff61b1e6
	v_mov_b32_e32 v95, 0xff61b1e6
	s_add_u32 s94, s62, 0x8f61000
	s_addc_u32 s95, s63, 0
	s_add_u32 s96, s62, 0x18803000
	s_addc_u32 s97, s63, 0
	v_lshl_add_u64 v[206:207], v[206:207], 0, s[94:95]
	v_lshl_add_u64 v[204:205], v[204:205], 0, s[96:97]
	s_mov_b32 s94, 0x28000
	s_mov_b32 s95, 0
	s_mov_b32 s96, 0x402000
	s_mov_b32 s97, 0
	v_mov_b32_e32 v235, v230
	v_add_u32_e32 v234, 0x4800, v215
	v_lshlrev_b32_e32 v248, 1, v230
	v_add_u32_e32 v248, 0x4400, v248
	v_lshlrev_b32_e32 v249, 1, v215
	v_add_u32_e32 v249, 0x4800, v249
	v_xor_b32_e32 v236, 0x80000000, v201
	s_cmp_eq_u32 s85, 1
	s_cbranch_scc1 .Lan_327_h1
.Lan_327_h0:
	s_add_i32 s87, s90, 1
	ds_read_b128 v[64:67], v235
	ds_read_b128 v[68:71], v235 offset:32
	ds_read_b128 v[72:75], v235 offset:64
	ds_read_b128 v[76:79], v235 offset:96
	ds_read_b128 v[160:163], v234 offset:34816
	s_cmp_lt_i32 s87, s38
	s_cselect_b64 s[54:55], -1, 0
	s_cbranch_scc0 .Lan_329_h0
	v_lshl_add_u64 v[244:245], v[206:207], 0, s[94:95]
	global_load_dwordx4 v[128:131], v[206:207], off
	global_load_dwordx4 v[132:135], v[244:245], off
.Lan_329_h0:
	s_cmp_lt_i32 s90, s38
	s_cselect_b64 s[56:57], -1, 0
	s_cbranch_scc0 .Lan_331_h0
	v_lshl_add_u64 v[246:247], v[204:205], 0, s[96:97]
	global_load_dwordx4 v[136:139], v[204:205], off offset:3968
	global_load_dwordx4 v[140:143], v[246:247], off offset:3968
.Lan_331_h0:
	v_cvt_f32_i32_e32 v237, v231
	s_setprio 1
	s_waitcnt lgkmcnt(4)
	v_mfma_f32_32x32x16_bf16 v[96:111], v[64:67], v[112:115], v[96:111]
	ds_read_b128 v[244:247], v234 offset:34848
	v_exp_f32_e32 v80, v80
	v_exp_f32_e32 v81, v81
	v_add_f32_e32 v238, 0, v80
	v_add_f32_e32 v238, v238, v81
	s_waitcnt lgkmcnt(4)
	v_mfma_f32_32x32x16_bf16 v[96:111], v[68:71], v[116:119], v[96:111]
	ds_read_b128 v[64:67], v234 offset:39424
	v_exp_f32_e32 v82, v82
	v_exp_f32_e32 v83, v83
	v_add_f32_e32 v238, v238, v82
	v_add_f32_e32 v238, v238, v83
	s_waitcnt lgkmcnt(4)
	v_mfma_f32_32x32x16_bf16 v[96:111], v[72:75], v[120:123], v[96:111]
	ds_read_b128 v[68:71], v234 offset:39456
	v_exp_f32_e32 v84, v84
	v_exp_f32_e32 v85, v85
	v_add_f32_e32 v238, v238, v84
	v_add_f32_e32 v238, v238, v85
	s_waitcnt lgkmcnt(4)
	v_mfma_f32_32x32x16_bf16 v[96:111], v[76:79], v[124:127], v[96:111]
	ds_read_b128 v[72:75], v234 offset:44032
	v_exp_f32_e32 v86, v86
	v_exp_f32_e32 v87, v87
	v_add_f32_e32 v238, v238, v86
	v_add_f32_e32 v238, v238, v87
	s_waitcnt lgkmcnt(4)
	v_mfma_f32_32x32x16_bf16 v[48:63], v[160:163], v[144:147], v[48:63]
	ds_read_b128 v[76:79], v234 offset:44064
	v_cvt_pk_bf16_f32 v152, v80, v81
	v_cvt_pk_bf16_f32 v153, v82, v83
	v_cvt_pk_bf16_f32 v154, v84, v85
	v_cvt_pk_bf16_f32 v155, v86, v87
	v_add_f32_e32 v255, 0x42800000, v237
	v_fma_f32 v254, v236, v255, v253
	s_waitcnt lgkmcnt(4)
	v_mfma_f32_32x32x16_bf16 v[48:63], v[244:247], v[148:151], v[48:63]
	ds_read_b128 v[160:163], v234 offset:48640
	v_exp_f32_e32 v88, v88
	v_exp_f32_e32 v89, v89
	v_add_f32_e32 v238, v238, v88
	v_add_f32_e32 v238, v238, v89
	v_fmamk_f32 v80, v201, 0x42000000, v254
	v_fmamk_f32 v81, v201, 0x42040000, v254
	s_waitcnt lgkmcnt(4)
	v_mfma_f32_32x32x16_bf16 v[32:47], v[64:67], v[144:147], v[32:47]
	ds_read_b128 v[244:247], v234 offset:48672
	v_exp_f32_e32 v90, v90
	v_exp_f32_e32 v91, v91
	v_add_f32_e32 v238, v238, v90
	v_add_f32_e32 v238, v238, v91
	v_fmamk_f32 v82, v201, 0x42080000, v254
	v_fmamk_f32 v83, v201, 0x420c0000, v254
	s_waitcnt lgkmcnt(4)
	v_mfma_f32_32x32x16_bf16 v[32:47], v[68:71], v[148:151], v[32:47]
	ds_read_b128 v[64:67], v235 offset:8704
	v_exp_f32_e32 v92, v92
	v_exp_f32_e32 v93, v93
	v_add_f32_e32 v238, v238, v92
	v_add_f32_e32 v238, v238, v93
	v_fmamk_f32 v84, v201, 0x42100000, v254
	v_fmamk_f32 v85, v201, 0x42140000, v254
	s_waitcnt lgkmcnt(4)
	v_mfma_f32_32x32x16_bf16 v[16:31], v[72:75], v[144:147], v[16:31]
	ds_read_b128 v[68:71], v235 offset:8736
	v_exp_f32_e32 v94, v94
	v_exp_f32_e32 v95, v95
	v_add_f32_e32 v238, v238, v94
	v_add_f32_e32 v238, v238, v95
	v_fmamk_f32 v86, v201, 0x42180000, v254
	v_fmamk_f32 v87, v201, 0x421c0000, v254
	s_waitcnt lgkmcnt(4)
	v_mfma_f32_32x32x16_bf16 v[16:31], v[76:79], v[148:151], v[16:31]
	ds_read_b128 v[72:75], v235 offset:8768
	v_cvt_pk_bf16_f32 v156, v88, v89
	v_cvt_pk_bf16_f32 v157, v90, v91
	v_cvt_pk_bf16_f32 v158, v92, v93
	v_cvt_pk_bf16_f32 v159, v94, v95
	s_waitcnt lgkmcnt(4)
	v_mfma_f32_32x32x16_bf16 v[0:15], v[160:163], v[144:147], v[0:15]
	ds_read_b128 v[76:79], v235 offset:8800
	v_fmamk_f32 v88, v201, 0x42400000, v254
	v_fmamk_f32 v89, v201, 0x42440000, v254
	v_fmamk_f32 v90, v201, 0x42480000, v254
	v_fmamk_f32 v91, v201, 0x424c0000, v254
	v_add_f32_e32 v238, v238, v233
	s_waitcnt lgkmcnt(4)
	v_mfma_f32_32x32x16_bf16 v[0:15], v[244:247], v[148:151], v[0:15]
	ds_read_b128 v[160:163], v234 offset:34880
	v_fmamk_f32 v92, v201, 0x42500000, v254
	v_fmamk_f32 v93, v201, 0x42540000, v254
	v_fmamk_f32 v94, v201, 0x42580000, v254
	v_fmamk_f32 v95, v201, 0x425c0000, v254
	s_cmp_lt_u32 s90, 2
	s_cbranch_scc1 .LfixA_skip_h0_do
	s_cmp_lt_i32 s90, s38
	s_cbranch_scc1 .LfixA_skip_h0

.LfixB_skip_h0:
	s_andn2_b64 vcc, exec, s[54:55]
	s_cbranch_vccnz .Lan_343_h0
	s_and_b32 s89, s87, 1
	s_mulk_i32 s89, 0x4400
	v_add_u32_e32 v255, s89, v212
	s_waitcnt vmcnt(1)
	ds_write_b128 v255, v[128:131]
	s_waitcnt vmcnt(0)
	ds_write_b128 v255, v[132:135] offset:8704
.Lan_343_h0:
	s_andn2_b64 vcc, exec, s[56:57]
	s_cbranch_vccnz .Lan_345_h0
	s_and_b32 s88, s90, 1
	s_mulk_i32 s88, 0x4800
	v_add_u32_e32 v255, s88, v222
	s_waitcnt vmcnt(1)
	ds_write_b128 v255, v[136:139] offset:34816
	s_waitcnt vmcnt(0)
	ds_write_b128 v255, v[140:143] offset:44032
.Lan_345_h0:
	v_lshl_add_u64 v[204:205], v[204:205], 0, s[30:31]
	v_lshl_add_u64 v[206:207], v[206:207], 0, s[44:45]
	v_sub_u32_e32 v235, v248, v235
	v_sub_u32_e32 v234, v249, v234
	s_cmp_eq_u32 s86, s87
	v_add_u32_e32 v231, 64, v231
	s_waitcnt lgkmcnt(0)
	s_barrier
	s_cbranch_scc1 .LBB0_347
	s_mov_b32 s90, s87
	s_branch .Lan_327_h0

.Lan_331_h1:
	v_cvt_f32_i32_e32 v237, v231
	s_setprio 0
	s_waitcnt lgkmcnt(4)
	v_mfma_f32_32x32x16_bf16 v[96:111], v[64:67], v[112:115], v[96:111]
	ds_read_b128 v[244:247], v234 offset:34848
	v_exp_f32_e32 v80, v80
	v_exp_f32_e32 v81, v81
	v_add_f32_e32 v238, 0, v80
	v_add_f32_e32 v238, v238, v81
	s_waitcnt lgkmcnt(4)
	v_mfma_f32_32x32x16_bf16 v[96:111], v[68:71], v[116:119], v[96:111]
	ds_read_b128 v[64:67], v234 offset:39424
	v_exp_f32_e32 v82, v82
	v_exp_f32_e32 v83, v83
	v_add_f32_e32 v238, v238, v82
	v_add_f32_e32 v238, v238, v83
	s_waitcnt lgkmcnt(4)
	v_mfma_f32_32x32x16_bf16 v[96:111], v[72:75], v[120:123], v[96:111]
	ds_read_b128 v[68:71], v234 offset:39456
	v_exp_f32_e32 v84, v84
	v_exp_f32_e32 v85, v85
	v_add_f32_e32 v238, v238, v84
	v_add_f32_e32 v238, v238, v85
	s_waitcnt lgkmcnt(4)
	v_mfma_f32_32x32x16_bf16 v[96:111], v[76:79], v[124:127], v[96:111]
	ds_read_b128 v[72:75], v234 offset:44032
	v_exp_f32_e32 v86, v86
	v_exp_f32_e32 v87, v87
	v_add_f32_e32 v238, v238, v86
	v_add_f32_e32 v238, v238, v87
	s_waitcnt lgkmcnt(4)
	v_mfma_f32_32x32x16_bf16 v[48:63], v[160:163], v[144:147], v[48:63]
	ds_read_b128 v[76:79], v234 offset:44064
	v_cvt_pk_bf16_f32 v152, v80, v81
	v_cvt_pk_bf16_f32 v153, v82, v83
	v_cvt_pk_bf16_f32 v154, v84, v85
	v_cvt_pk_bf16_f32 v155, v86, v87
	v_add_f32_e32 v255, 0x42800000, v237
	v_fma_f32 v254, v236, v255, v253
	s_waitcnt lgkmcnt(4)
	v_mfma_f32_32x32x16_bf16 v[48:63], v[244:247], v[148:151], v[48:63]
	ds_read_b128 v[160:163], v234 offset:48640
	v_exp_f32_e32 v88, v88
	v_exp_f32_e32 v89, v89
	v_add_f32_e32 v238, v238, v88
	v_add_f32_e32 v238, v238, v89
	v_fmamk_f32 v80, v201, 0x42000000, v254
	v_fmamk_f32 v81, v201, 0x42040000, v254
	s_waitcnt lgkmcnt(4)
	v_mfma_f32_32x32x16_bf16 v[32:47], v[64:67], v[144:147], v[32:47]
	ds_read_b128 v[244:247], v234 offset:48672
	v_exp_f32_e32 v90, v90
	v_exp_f32_e32 v91, v91
	v_add_f32_e32 v238, v238, v90
	v_add_f32_e32 v238, v238, v91
	v_fmamk_f32 v82, v201, 0x42080000, v254
	v_fmamk_f32 v83, v201, 0x420c0000, v254
	s_waitcnt lgkmcnt(4)
	v_mfma_f32_32x32x16_bf16 v[32:47], v[68:71], v[148:151], v[32:47]
	ds_read_b128 v[64:67], v235 offset:8704
	v_exp_f32_e32 v92, v92
	v_exp_f32_e32 v93, v93
	v_add_f32_e32 v238, v238, v92
	v_add_f32_e32 v238, v238, v93
	v_fmamk_f32 v84, v201, 0x42100000, v254
	v_fmamk_f32 v85, v201, 0x42140000, v254
	s_waitcnt lgkmcnt(4)
	v_mfma_f32_32x32x16_bf16 v[16:31], v[72:75], v[144:147], v[16:31]
	ds_read_b128 v[68:71], v235 offset:8736
	v_exp_f32_e32 v94, v94
	v_exp_f32_e32 v95, v95
	v_add_f32_e32 v238, v238, v94
	v_add_f32_e32 v238, v238, v95
	v_fmamk_f32 v86, v201, 0x42180000, v254
	v_fmamk_f32 v87, v201, 0x421c0000, v254
	s_waitcnt lgkmcnt(4)
	v_mfma_f32_32x32x16_bf16 v[16:31], v[76:79], v[148:151], v[16:31]
	ds_read_b128 v[72:75], v235 offset:8768
	v_cvt_pk_bf16_f32 v156, v88, v89
	v_cvt_pk_bf16_f32 v157, v90, v91
	v_cvt_pk_bf16_f32 v158, v92, v93
	v_cvt_pk_bf16_f32 v159, v94, v95
	s_waitcnt lgkmcnt(4)
	v_mfma_f32_32x32x16_bf16 v[0:15], v[160:163], v[144:147], v[0:15]
	ds_read_b128 v[76:79], v235 offset:8800
	v_fmamk_f32 v88, v201, 0x42400000, v254
	v_fmamk_f32 v89, v201, 0x42440000, v254
	v_fmamk_f32 v90, v201, 0x42480000, v254
	v_fmamk_f32 v91, v201, 0x424c0000, v254
	v_add_f32_e32 v238, v238, v233
	s_waitcnt lgkmcnt(4)
	v_mfma_f32_32x32x16_bf16 v[0:15], v[244:247], v[148:151], v[0:15]
	ds_read_b128 v[160:163], v234 offset:34880
	v_fmamk_f32 v92, v201, 0x42500000, v254
	v_fmamk_f32 v93, v201, 0x42540000, v254
	v_fmamk_f32 v94, v201, 0x42580000, v254
	v_fmamk_f32 v95, v201, 0x425c0000, v254
	s_cmp_lt_u32 s90, 2
	s_cbranch_scc1 .LfixA_skip_h1_do
	s_cmp_lt_i32 s90, s38
	s_cbranch_scc1 .LfixA_skip_h1
